# proj K-loop: exact counted vmcnt in every iteration (the conservative waits drained loads issued half an iteration earlier)
# baseline (speedup 1.0000x reference)
.Lpq_a1:
	s_cmp_eq_u32 s44, 4
	s_cbranch_scc1 .Lpq_m1
	s_cmp_eq_u32 s44, 8
	s_cbranch_scc1 .Lpq_m1
	s_cmp_lt_u32 s42, 17
	s_cbranch_scc1 .Lpq_b1
	s_waitcnt vmcnt(3)
	ds_write_b128 v188, v[34:37] offset:32768
	s_waitcnt vmcnt(2)
	ds_write_b128 v188, v[38:41] offset:40960
	s_waitcnt vmcnt(1)
	ds_write_b128 v188, v[50:53] offset:49152
	s_waitcnt vmcnt(0)
	ds_write_b128 v188, v[58:61] offset:57344
	s_branch .Lpq_j1
.Lpq_b1:
	s_waitcnt vmcnt(7)
	ds_write_b128 v188, v[34:37] offset:32768
	s_waitcnt vmcnt(6)
	ds_write_b128 v188, v[38:41] offset:40960
	s_waitcnt vmcnt(5)
	ds_write_b128 v188, v[50:53] offset:49152
	s_waitcnt vmcnt(4)
	ds_write_b128 v188, v[58:61] offset:57344
	s_branch .Lpq_j1

.Lpq_a2:
	s_cmp_eq_u32 s44, 4
	s_cbranch_scc1 .Lpq_m2
	s_cmp_eq_u32 s44, 8
	s_cbranch_scc1 .Lpq_m2
	s_waitcnt vmcnt(7)
	ds_write_b128 v188, v[42:45]
	s_waitcnt vmcnt(6)
	ds_write_b128 v188, v[46:49] offset:8192
	s_waitcnt vmcnt(5)
	ds_write_b128 v188, v[54:57] offset:16384
	s_waitcnt vmcnt(4)
	ds_write_b128 v188, v[62:65] offset:24576
	s_branch .Lpq_j2
